# MLA k/v up-projection hand-written: 32-row latent slab per wave in registers, weight blocks through a 2-slot LDS ring, row-per-lane epilogue with permlane32 swaps and 16-B stores, balanced contiguous
# speedup vs baseline: 1.0097x; 1.0097x over previous
.LBB0_417:
	s_or_b64 exec, exec, s[0:1]
	s_waitcnt lgkmcnt(0)
	v_mov_b32_e32 v0, v143
	s_and_b64 vcc, exec, s[72:73]
	s_barrier
	v_and_b32_e32 v249, 31, v143
	v_bfe_u32 v250, v143, 5, 1
	v_lshrrev_b32_e32 v251, 6, v143
	v_lshl_add_u32 v251, v251, 5, v249
	v_mul_u32_u24_e32 v242, 0x1440, v251
	v_lshl_add_u32 v242, v250, 4, v242
	v_lshlrev_b32_e32 v243, 3, v251
	v_add_u32_e32 v243, 4, v243
	v_mul_u32_u24_e32 v244, 192, v251
	v_lshl_add_u32 v244, v250, 5, v244
	v_lshlrev_b32_e32 v245, 7, v251
	v_lshl_add_u32 v245, v250, 5, v245
	v_lshrrev_b32_e32 v246, 4, v143
	v_mul_u32_u24_e32 v246, 272, v246
	v_and_b32_e32 v247, 15, v143
	v_lshl_add_u32 v246, v247, 4, v246
	v_lshlrev_b32_e32 v247, 4, v143
	v_mul_u32_u24_e32 v248, 272, v249
	v_lshl_add_u32 v248, v250, 4, v248
	v_readlane_b32 s0, v253, 0
	s_and_b32 s1, s0, 7
	s_lshl_b32 s1, s1, 5
	s_lshr_b32 s0, s0, 3
	s_add_u32 s0, s0, s1
	s_mul_i32 s4, s0, 3264
	s_lshr_b32 s4, s4, 8
	s_add_u32 s0, s0, 1
	s_mul_i32 s5, s0, 3264
	s_lshr_b32 s5, s5, 8
	s_mul_i32 s0, s74, 196608
	s_add_u32 s0, s0, 0xba0000
	s_add_u32 s8, s50, s0
	s_addc_u32 s9, s51, 0
	s_mul_hi_u32 s59, s4, 0xaaaaaaab
	s_lshr_b32 s59, s59, 4
	s_add_u32 s6, s59, 1
	s_mul_i32 s6, s6, 24
	s_min_u32 s6, s6, s5
	s_lshl_b32 s32, s59, 8
	s_lshr_b32 s54, s32, 12
	s_and_b32 s55, s32, 0xfff
	s_sub_u32 s56, s32, 0x8000
	s_lshr_b32 s56, s56, 8
	s_movk_i32 s58, 0x1000
	s_cmp_lt_u32 s32, 0x8000
	s_cselect_b32 s54, s54, s56
	s_cselect_b32 s55, s55, s58
	s_mul_i32 s54, s54, 26112
	s_add_u32 s18, s54, s55
	s_mul_i32 s54, s32, 5184
	s_add_u32 s54, s54, 0x5cbd200
	s_add_u32 s20, s50, s54
	s_addc_u32 s21, s51, 0
	s_lshl_b32 s54, s32, 3
	s_add_u32 s54, s54, 0x1079000
	s_add_u32 s26, s50, s54
	s_addc_u32 s27, s51, 0
	s_add_u32 s59, s59, 1
	s_min_u32 s59, s59, 135
	s_lshl_b32 s32, s59, 8
	s_lshr_b32 s54, s32, 12
	s_and_b32 s55, s32, 0xfff
	s_sub_u32 s56, s32, 0x8000
	s_lshr_b32 s56, s56, 8
	s_movk_i32 s58, 0x1000
	s_cmp_lt_u32 s32, 0x8000
	s_cselect_b32 s54, s54, s56
	s_cselect_b32 s55, s55, s58
	s_mul_i32 s54, s54, 26112
	s_add_u32 s19, s54, s55
	s_mul_i32 s54, s32, 5184
	s_add_u32 s54, s54, 0x5cbd200
	s_add_u32 s22, s50, s54
	s_addc_u32 s23, s51, 0
	s_lshl_b32 s54, s32, 3
	s_add_u32 s54, s54, 0x1079000
	s_add_u32 s30, s50, s54
	s_addc_u32 s31, s51, 0
	global_load_dwordx4 v[96:99], v242, s[20:21] offset:0
	global_load_dwordx4 v[100:103], v242, s[20:21] offset:32
	global_load_dwordx4 v[104:107], v242, s[20:21] offset:64
	global_load_dwordx4 v[108:111], v242, s[20:21] offset:96
	global_load_dwordx4 v[112:115], v242, s[20:21] offset:128
	global_load_dwordx4 v[116:119], v242, s[20:21] offset:160
	global_load_dwordx4 v[120:123], v242, s[20:21] offset:192
	global_load_dwordx4 v[124:127], v242, s[20:21] offset:224
	global_load_dword v152, v243, s[26:27]
	global_load_dwordx4 v[48:51], v242, s[22:23] offset:0
	global_load_dwordx4 v[52:55], v242, s[22:23] offset:32
	global_load_dwordx4 v[56:59], v242, s[22:23] offset:64
	global_load_dwordx4 v[60:63], v242, s[22:23] offset:96
	global_load_dwordx4 v[64:67], v242, s[22:23] offset:128
	global_load_dwordx4 v[68:71], v242, s[22:23] offset:160
	global_load_dwordx4 v[72:75], v242, s[22:23] offset:192
	global_load_dwordx4 v[76:79], v242, s[22:23] offset:224
	global_load_dword v153, v243, s[30:31]
	s_mov_b32 s25, s4
	s_add_u32 s0, s5, -1
	s_min_u32 s0, s25, s0
	s_mul_hi_u32 s1, s0, 0xaaaaaaab
	s_lshr_b32 s1, s1, 4
	s_mul_i32 s1, s1, 24
	s_sub_u32 s0, s0, s1
	s_lshl_b32 s0, s0, 13
	s_add_u32 s10, s8, s0
	s_addc_u32 s11, s9, 0
	global_load_dwordx4 v[220:223], v247, s[10:11]
	s_add_u32 s25, s25, 1
	s_add_u32 s0, s5, -1
	s_min_u32 s0, s25, s0
	s_mul_hi_u32 s1, s0, 0xaaaaaaab
	s_lshr_b32 s1, s1, 4
	s_mul_i32 s1, s1, 24
	s_sub_u32 s0, s0, s1
	s_lshl_b32 s0, s0, 13
	s_add_u32 s10, s8, s0
	s_addc_u32 s11, s9, 0
	global_load_dwordx4 v[224:227], v247, s[10:11]
	s_add_u32 s25, s25, 1
	s_add_u32 s0, s5, -1
	s_min_u32 s0, s25, s0
	s_mul_hi_u32 s1, s0, 0xaaaaaaab
	s_lshr_b32 s1, s1, 4
	s_mul_i32 s1, s1, 24
	s_sub_u32 s0, s0, s1
	s_lshl_b32 s0, s0, 13
	s_add_u32 s10, s8, s0
	s_addc_u32 s11, s9, 0
	global_load_dwordx4 v[228:231], v247, s[10:11]
	s_add_u32 s25, s25, 1
	s_add_u32 s0, s5, -1
	s_min_u32 s0, s25, s0
	s_mul_hi_u32 s1, s0, 0xaaaaaaab
	s_lshr_b32 s1, s1, 4
	s_mul_i32 s1, s1, 24
	s_sub_u32 s0, s0, s1
	s_lshl_b32 s0, s0, 13
	s_add_u32 s10, s8, s0
	s_addc_u32 s11, s9, 0
	global_load_dwordx4 v[238:241], v247, s[10:11]
	s_add_u32 s25, s25, 1
	s_waitcnt vmcnt(0)
	v_mov_b32_e32 v154, v152
	v_mov_b32_e32 v155, v152
	ds_write_b128 v246, v[220:223]
	s_add_u32 s0, s5, -1
	s_min_u32 s0, s25, s0
	s_mul_hi_u32 s1, s0, 0xaaaaaaab
	s_lshr_b32 s1, s1, 4
	s_mul_i32 s1, s1, 24
	s_sub_u32 s0, s0, s1
	s_lshl_b32 s0, s0, 13
	s_add_u32 s10, s8, s0
	s_addc_u32 s11, s9, 0
	global_load_dwordx4 v[220:223], v247, s[10:11]
	s_add_u32 s25, s25, 1
	global_load_dword v156, v243, s[26:27]
	global_load_dword v157, v243, s[26:27]
	s_waitcnt lgkmcnt(0)
	s_barrier
	s_mov_b32 s16, 2
.Lkv_loop:
	s_waitcnt vmcnt(11)
	ds_write_b128 v246, v[224:227] offset:8704
	s_add_u32 s0, s5, -1
	s_min_u32 s0, s25, s0
	s_mul_hi_u32 s1, s0, 0xaaaaaaab
	s_lshr_b32 s1, s1, 4
	s_mul_i32 s1, s1, 24
	s_sub_u32 s0, s0, s1
	s_lshl_b32 s0, s0, 13
	s_add_u32 s10, s8, s0
	s_addc_u32 s11, s9, 0
	global_load_dwordx4 v[224:227], v247, s[10:11]
	s_add_u32 s25, s25, 1
	s_mul_hi_u32 s1, s4, 0xaaaaaaab
	s_lshr_b32 s1, s1, 4
	s_mul_i32 s1, s1, 24
	s_sub_u32 s0, s4, s1
	s_lshr_b32 s1, s0, 2
	s_mul_i32 s1, s1, 4352
	s_add_u32 s1, s1, s18
	s_and_b32 s0, s0, 3
	s_lshl_b32 s32, s0, 6
	s_mul_i32 s54, s1, 192
	s_add_u32 s54, s54, s32
	s_add_u32 s54, s54, 0x12f1d000
	s_lshl_b32 s55, s1, 7
	s_add_u32 s55, s55, s32
	s_add_u32 s55, s55, 0x1555cf80
	s_cmp_lt_u32 s0, 2
	s_cselect_b32 s54, s54, s55
	s_cselect_b32 s17, 0, 1
	s_add_u32 s14, s50, s54
	s_addc_u32 s15, s51, 0
	ds_read_b128 v[188:191], v248 offset:0
	ds_read_b128 v[192:195], v248 offset:32
	ds_read_b128 v[196:199], v248 offset:64
	ds_read_b128 v[200:203], v248 offset:96
	ds_read_b128 v[204:207], v248 offset:128
	ds_read_b128 v[208:211], v248 offset:160
	ds_read_b128 v[212:215], v248 offset:192
	ds_read_b128 v[216:219], v248 offset:224
	s_waitcnt lgkmcnt(7)
	v_mfma_f32_32x32x16_bf16 v[0:15], v[188:191], v[96:99], 0
	s_waitcnt lgkmcnt(6)
	v_mfma_f32_32x32x16_bf16 v[0:15], v[192:195], v[100:103], v[0:15]
	s_waitcnt lgkmcnt(5)
	v_mfma_f32_32x32x16_bf16 v[0:15], v[196:199], v[104:107], v[0:15]
	s_waitcnt lgkmcnt(4)
	v_mfma_f32_32x32x16_bf16 v[0:15], v[200:203], v[108:111], v[0:15]
	s_waitcnt lgkmcnt(3)
	v_mfma_f32_32x32x16_bf16 v[0:15], v[204:207], v[112:115], v[0:15]
	s_waitcnt lgkmcnt(2)
	v_mfma_f32_32x32x16_bf16 v[0:15], v[208:211], v[116:119], v[0:15]
	s_waitcnt lgkmcnt(1)
	v_mfma_f32_32x32x16_bf16 v[0:15], v[212:215], v[120:123], v[0:15]
	s_waitcnt lgkmcnt(0)
	v_mfma_f32_32x32x16_bf16 v[0:15], v[216:219], v[124:127], v[0:15]
	s_cmp_eq_u32 s16, 2
	s_cbranch_scc0 .Lkv_ep0
	global_load_dword v156, v243, s[26:27]
	global_load_dword v157, v243, s[26:27]
	s_branch .Lkv_ex0
.Lkv_ep0:
	v_mul_f32_e32 v16, v16, v155
	v_mul_f32_e32 v17, v17, v155
	v_mul_f32_e32 v18, v18, v155
	v_mul_f32_e32 v19, v19, v155
	v_mul_f32_e32 v20, v20, v155
	v_mul_f32_e32 v21, v21, v155
	v_mul_f32_e32 v22, v22, v155
	v_mul_f32_e32 v23, v23, v155
	v_mul_f32_e32 v24, v24, v155
	v_mul_f32_e32 v25, v25, v155
	v_mul_f32_e32 v26, v26, v155
	v_mul_f32_e32 v27, v27, v155
	v_mul_f32_e32 v28, v28, v155
	v_mul_f32_e32 v29, v29, v155
	v_mul_f32_e32 v30, v30, v155
	v_mul_f32_e32 v31, v31, v155
	v_cvt_pk_bf16_f32 v144, v16, v17
	v_cvt_pk_bf16_f32 v145, v18, v19
	v_cvt_pk_bf16_f32 v148, v20, v21
	v_cvt_pk_bf16_f32 v149, v22, v23
	v_cvt_pk_bf16_f32 v146, v24, v25
	v_cvt_pk_bf16_f32 v147, v26, v27
	v_cvt_pk_bf16_f32 v150, v28, v29
	v_cvt_pk_bf16_f32 v151, v30, v31
	s_nop 1
	v_permlane32_swap_b32_e32 v144, v146
	v_permlane32_swap_b32_e32 v145, v147
	v_permlane32_swap_b32_e32 v148, v150
	v_permlane32_swap_b32_e32 v149, v151
	s_cmp_eq_u32 s16, 0
	s_cbranch_scc0 .Lkv_ev0
	global_store_dwordx4 v244, v[144:147], s[12:13]
	global_store_dwordx4 v244, v[148:151], s[12:13] offset:16
	s_branch .Lkv_ee0
.Lkv_ev0:
	global_store_dwordx4 v245, v[144:147], s[12:13]
	global_store_dwordx4 v245, v[148:151], s[12:13] offset:16
.Lkv_ee0:
.Lkv_ex0:
	v_mov_b32_e32 v155, v154
	s_mov_b64 s[12:13], s[14:15]
	s_mov_b32 s16, s17
	s_add_u32 s4, s4, 1
	s_waitcnt lgkmcnt(0)
	s_barrier
	s_cmp_ge_u32 s4, s5
	s_cbranch_scc1 .Lkv_drain0
	s_cmp_lg_u32 s4, s6
	s_cbranch_scc1 .Lkv_ns0
	s_nop 7
	s_nop 7
	s_nop 7
	s_nop 7
	v_mov_b32_e32 v96, v48
	v_mov_b32_e32 v97, v49
	v_mov_b32_e32 v98, v50
	v_mov_b32_e32 v99, v51
	v_mov_b32_e32 v100, v52
	v_mov_b32_e32 v101, v53
	v_mov_b32_e32 v102, v54
	v_mov_b32_e32 v103, v55
	v_mov_b32_e32 v104, v56
	v_mov_b32_e32 v105, v57
	v_mov_b32_e32 v106, v58
	v_mov_b32_e32 v107, v59
	v_mov_b32_e32 v108, v60
	v_mov_b32_e32 v109, v61
	v_mov_b32_e32 v110, v62
	v_mov_b32_e32 v111, v63
	v_mov_b32_e32 v112, v64
	v_mov_b32_e32 v113, v65
	v_mov_b32_e32 v114, v66
	v_mov_b32_e32 v115, v67
	v_mov_b32_e32 v116, v68
	v_mov_b32_e32 v117, v69
	v_mov_b32_e32 v118, v70
	v_mov_b32_e32 v119, v71
	v_mov_b32_e32 v120, v72
	v_mov_b32_e32 v121, v73
	v_mov_b32_e32 v122, v74
	v_mov_b32_e32 v123, v75
	v_mov_b32_e32 v124, v76
	v_mov_b32_e32 v125, v77
	v_mov_b32_e32 v126, v78
	v_mov_b32_e32 v127, v79
	v_mov_b32_e32 v154, v153
	s_mov_b32 s18, s19
	s_mov_b32 s6, s5
.Lkv_ns0:
	s_waitcnt vmcnt(11)
	ds_write_b128 v246, v[228:231] offset:0
	s_add_u32 s0, s5, -1
	s_min_u32 s0, s25, s0
	s_mul_hi_u32 s1, s0, 0xaaaaaaab
	s_lshr_b32 s1, s1, 4
	s_mul_i32 s1, s1, 24
	s_sub_u32 s0, s0, s1
	s_lshl_b32 s0, s0, 13
	s_add_u32 s10, s8, s0
	s_addc_u32 s11, s9, 0
	global_load_dwordx4 v[228:231], v247, s[10:11]
	s_add_u32 s25, s25, 1
	s_mul_hi_u32 s1, s4, 0xaaaaaaab
	s_lshr_b32 s1, s1, 4
	s_mul_i32 s1, s1, 24
	s_sub_u32 s0, s4, s1
	s_lshr_b32 s1, s0, 2
	s_mul_i32 s1, s1, 4352
	s_add_u32 s1, s1, s18
	s_and_b32 s0, s0, 3
	s_lshl_b32 s32, s0, 6
	s_mul_i32 s54, s1, 192
	s_add_u32 s54, s54, s32
	s_add_u32 s54, s54, 0x12f1d000
	s_lshl_b32 s55, s1, 7
	s_add_u32 s55, s55, s32
	s_add_u32 s55, s55, 0x1555cf80
	s_cmp_lt_u32 s0, 2
	s_cselect_b32 s54, s54, s55
	s_cselect_b32 s17, 0, 1
	s_add_u32 s14, s50, s54
	s_addc_u32 s15, s51, 0
	ds_read_b128 v[188:191], v248 offset:8704
	ds_read_b128 v[192:195], v248 offset:8736
	ds_read_b128 v[196:199], v248 offset:8768
	ds_read_b128 v[200:203], v248 offset:8800
	ds_read_b128 v[204:207], v248 offset:8832
	ds_read_b128 v[208:211], v248 offset:8864
	ds_read_b128 v[212:215], v248 offset:8896
	ds_read_b128 v[216:219], v248 offset:8928
	s_waitcnt lgkmcnt(7)
	v_mfma_f32_32x32x16_bf16 v[16:31], v[188:191], v[96:99], 0
	s_waitcnt lgkmcnt(6)
	v_mfma_f32_32x32x16_bf16 v[16:31], v[192:195], v[100:103], v[16:31]
	s_waitcnt lgkmcnt(5)
	v_mfma_f32_32x32x16_bf16 v[16:31], v[196:199], v[104:107], v[16:31]
	s_waitcnt lgkmcnt(4)
	v_mfma_f32_32x32x16_bf16 v[16:31], v[200:203], v[108:111], v[16:31]
	s_waitcnt lgkmcnt(3)
	v_mfma_f32_32x32x16_bf16 v[16:31], v[204:207], v[112:115], v[16:31]
	s_waitcnt lgkmcnt(2)
	v_mfma_f32_32x32x16_bf16 v[16:31], v[208:211], v[116:119], v[16:31]
	s_waitcnt lgkmcnt(1)
	v_mfma_f32_32x32x16_bf16 v[16:31], v[212:215], v[120:123], v[16:31]
	s_waitcnt lgkmcnt(0)
	v_mfma_f32_32x32x16_bf16 v[16:31], v[216:219], v[124:127], v[16:31]
	s_cmp_eq_u32 s16, 2
	s_cbranch_scc0 .Lkv_ep1
	global_load_dword v156, v243, s[26:27]
	global_load_dword v157, v243, s[26:27]
	s_branch .Lkv_ex1
.Lkv_ep1:
	v_mul_f32_e32 v0, v0, v155
	v_mul_f32_e32 v1, v1, v155
	v_mul_f32_e32 v2, v2, v155
	v_mul_f32_e32 v3, v3, v155
	v_mul_f32_e32 v4, v4, v155
	v_mul_f32_e32 v5, v5, v155
	v_mul_f32_e32 v6, v6, v155
	v_mul_f32_e32 v7, v7, v155
	v_mul_f32_e32 v8, v8, v155
	v_mul_f32_e32 v9, v9, v155
	v_mul_f32_e32 v10, v10, v155
	v_mul_f32_e32 v11, v11, v155
	v_mul_f32_e32 v12, v12, v155
	v_mul_f32_e32 v13, v13, v155
	v_mul_f32_e32 v14, v14, v155
	v_mul_f32_e32 v15, v15, v155
	v_cvt_pk_bf16_f32 v144, v0, v1
	v_cvt_pk_bf16_f32 v145, v2, v3
	v_cvt_pk_bf16_f32 v148, v4, v5
	v_cvt_pk_bf16_f32 v149, v6, v7
	v_cvt_pk_bf16_f32 v146, v8, v9
	v_cvt_pk_bf16_f32 v147, v10, v11
	v_cvt_pk_bf16_f32 v150, v12, v13
	v_cvt_pk_bf16_f32 v151, v14, v15
	s_nop 1
	v_permlane32_swap_b32_e32 v144, v146
	v_permlane32_swap_b32_e32 v145, v147
	v_permlane32_swap_b32_e32 v148, v150
	v_permlane32_swap_b32_e32 v149, v151
	s_cmp_eq_u32 s16, 0
	s_cbranch_scc0 .Lkv_ev1
	global_store_dwordx4 v244, v[144:147], s[12:13]
	global_store_dwordx4 v244, v[148:151], s[12:13] offset:16
	s_branch .Lkv_ee1

.Lkv_ns1:
	s_waitcnt vmcnt(11)
	ds_write_b128 v246, v[238:241] offset:8704
	s_add_u32 s0, s5, -1
	s_min_u32 s0, s25, s0
	s_mul_hi_u32 s1, s0, 0xaaaaaaab
	s_lshr_b32 s1, s1, 4
	s_mul_i32 s1, s1, 24
	s_sub_u32 s0, s0, s1
	s_lshl_b32 s0, s0, 13
	s_add_u32 s10, s8, s0
	s_addc_u32 s11, s9, 0
	global_load_dwordx4 v[238:241], v247, s[10:11]
	s_add_u32 s25, s25, 1
	s_mul_hi_u32 s1, s4, 0xaaaaaaab
	s_lshr_b32 s1, s1, 4
	s_mul_i32 s1, s1, 24
	s_sub_u32 s0, s4, s1
	s_lshr_b32 s1, s0, 2
	s_mul_i32 s1, s1, 4352
	s_add_u32 s1, s1, s18
	s_and_b32 s0, s0, 3
	s_lshl_b32 s32, s0, 6
	s_mul_i32 s54, s1, 192
	s_add_u32 s54, s54, s32
	s_add_u32 s54, s54, 0x12f1d000
	s_lshl_b32 s55, s1, 7
	s_add_u32 s55, s55, s32
	s_add_u32 s55, s55, 0x1555cf80
	s_cmp_lt_u32 s0, 2
	s_cselect_b32 s54, s54, s55
	s_cselect_b32 s17, 0, 1
	s_add_u32 s14, s50, s54
	s_addc_u32 s15, s51, 0
	ds_read_b128 v[188:191], v248 offset:0
	ds_read_b128 v[192:195], v248 offset:32
	ds_read_b128 v[196:199], v248 offset:64
	ds_read_b128 v[200:203], v248 offset:96
	ds_read_b128 v[204:207], v248 offset:128
	ds_read_b128 v[208:211], v248 offset:160
	ds_read_b128 v[212:215], v248 offset:192
	ds_read_b128 v[216:219], v248 offset:224
	s_waitcnt lgkmcnt(7)
	v_mfma_f32_32x32x16_bf16 v[0:15], v[188:191], v[96:99], 0
	s_waitcnt lgkmcnt(6)
	v_mfma_f32_32x32x16_bf16 v[0:15], v[192:195], v[100:103], v[0:15]
	s_waitcnt lgkmcnt(5)
	v_mfma_f32_32x32x16_bf16 v[0:15], v[196:199], v[104:107], v[0:15]
	s_waitcnt lgkmcnt(4)
	v_mfma_f32_32x32x16_bf16 v[0:15], v[200:203], v[108:111], v[0:15]
	s_waitcnt lgkmcnt(3)
	v_mfma_f32_32x32x16_bf16 v[0:15], v[204:207], v[112:115], v[0:15]
	s_waitcnt lgkmcnt(2)
	v_mfma_f32_32x32x16_bf16 v[0:15], v[208:211], v[116:119], v[0:15]
	s_waitcnt lgkmcnt(1)
	v_mfma_f32_32x32x16_bf16 v[0:15], v[212:215], v[120:123], v[0:15]
	s_waitcnt lgkmcnt(0)
	v_mfma_f32_32x32x16_bf16 v[0:15], v[216:219], v[124:127], v[0:15]
	s_cmp_eq_u32 s16, 2
	s_cbranch_scc0 .Lkv_ep2
	global_load_dword v156, v243, s[26:27]
	global_load_dword v157, v243, s[26:27]
	s_branch .Lkv_ex2

.Lkv_ns2:
	s_waitcnt vmcnt(11)
	ds_write_b128 v246, v[220:223] offset:0
	s_add_u32 s0, s5, -1
	s_min_u32 s0, s25, s0
	s_mul_hi_u32 s1, s0, 0xaaaaaaab
	s_lshr_b32 s1, s1, 4
	s_mul_i32 s1, s1, 24
	s_sub_u32 s0, s0, s1
	s_lshl_b32 s0, s0, 13
	s_add_u32 s10, s8, s0
	s_addc_u32 s11, s9, 0
	global_load_dwordx4 v[220:223], v247, s[10:11]
	s_add_u32 s25, s25, 1
	s_mul_hi_u32 s1, s4, 0xaaaaaaab
	s_lshr_b32 s1, s1, 4
	s_mul_i32 s1, s1, 24
	s_sub_u32 s0, s4, s1
	s_lshr_b32 s1, s0, 2
	s_mul_i32 s1, s1, 4352
	s_add_u32 s1, s1, s18
	s_and_b32 s0, s0, 3
	s_lshl_b32 s32, s0, 6
	s_mul_i32 s54, s1, 192
	s_add_u32 s54, s54, s32
	s_add_u32 s54, s54, 0x12f1d000
	s_lshl_b32 s55, s1, 7
	s_add_u32 s55, s55, s32
	s_add_u32 s55, s55, 0x1555cf80
	s_cmp_lt_u32 s0, 2
	s_cselect_b32 s54, s54, s55
	s_cselect_b32 s17, 0, 1
	s_add_u32 s14, s50, s54
	s_addc_u32 s15, s51, 0
	ds_read_b128 v[188:191], v248 offset:8704
	ds_read_b128 v[192:195], v248 offset:8736
	ds_read_b128 v[196:199], v248 offset:8768
	ds_read_b128 v[200:203], v248 offset:8800
	ds_read_b128 v[204:207], v248 offset:8832
	ds_read_b128 v[208:211], v248 offset:8864
	ds_read_b128 v[212:215], v248 offset:8896
	ds_read_b128 v[216:219], v248 offset:8928
	s_waitcnt lgkmcnt(7)
	v_mfma_f32_32x32x16_bf16 v[16:31], v[188:191], v[96:99], 0
	s_waitcnt lgkmcnt(6)
	v_mfma_f32_32x32x16_bf16 v[16:31], v[192:195], v[100:103], v[16:31]
	s_waitcnt lgkmcnt(5)
	v_mfma_f32_32x32x16_bf16 v[16:31], v[196:199], v[104:107], v[16:31]
	s_waitcnt lgkmcnt(4)
	v_mfma_f32_32x32x16_bf16 v[16:31], v[200:203], v[108:111], v[16:31]
	s_waitcnt lgkmcnt(3)
	v_mfma_f32_32x32x16_bf16 v[16:31], v[204:207], v[112:115], v[16:31]
	s_waitcnt lgkmcnt(2)
	v_mfma_f32_32x32x16_bf16 v[16:31], v[208:211], v[116:119], v[16:31]
	s_waitcnt lgkmcnt(1)
	v_mfma_f32_32x32x16_bf16 v[16:31], v[212:215], v[120:123], v[16:31]
	s_waitcnt lgkmcnt(0)
	v_mfma_f32_32x32x16_bf16 v[16:31], v[216:219], v[124:127], v[16:31]
	s_cmp_eq_u32 s16, 2
	s_cbranch_scc0 .Lkv_ep3
	global_load_dword v156, v243, s[26:27]
	global_load_dword v157, v243, s[26:27]
	s_branch .Lkv_ex3

.Lkv_drain0:
	s_nop 7
	s_nop 7
	v_mul_f32_e32 v0, v0, v155
	v_mul_f32_e32 v1, v1, v155
	v_mul_f32_e32 v2, v2, v155
	v_mul_f32_e32 v3, v3, v155
	v_mul_f32_e32 v4, v4, v155
	v_mul_f32_e32 v5, v5, v155
	v_mul_f32_e32 v6, v6, v155
	v_mul_f32_e32 v7, v7, v155
	v_mul_f32_e32 v8, v8, v155
	v_mul_f32_e32 v9, v9, v155
	v_mul_f32_e32 v10, v10, v155
	v_mul_f32_e32 v11, v11, v155
	v_mul_f32_e32 v12, v12, v155
	v_mul_f32_e32 v13, v13, v155
	v_mul_f32_e32 v14, v14, v155
	v_mul_f32_e32 v15, v15, v155
	v_cvt_pk_bf16_f32 v144, v0, v1
	v_cvt_pk_bf16_f32 v145, v2, v3
	v_cvt_pk_bf16_f32 v148, v4, v5
	v_cvt_pk_bf16_f32 v149, v6, v7
	v_cvt_pk_bf16_f32 v146, v8, v9
	v_cvt_pk_bf16_f32 v147, v10, v11
	v_cvt_pk_bf16_f32 v150, v12, v13
	v_cvt_pk_bf16_f32 v151, v14, v15
	s_nop 1
	v_permlane32_swap_b32_e32 v144, v146
	v_permlane32_swap_b32_e32 v145, v147
	v_permlane32_swap_b32_e32 v148, v150
	v_permlane32_swap_b32_e32 v149, v151
	s_cmp_eq_u32 s16, 0
	s_cbranch_scc0 .Lkv_evd0
	global_store_dwordx4 v244, v[144:147], s[12:13]
	global_store_dwordx4 v244, v[148:151], s[12:13] offset:16
	s_branch .Lkv_eed0

.Lkv_drain1:
	s_nop 7
	s_nop 7
	v_mul_f32_e32 v16, v16, v155
	v_mul_f32_e32 v17, v17, v155
	v_mul_f32_e32 v18, v18, v155
	v_mul_f32_e32 v19, v19, v155
	v_mul_f32_e32 v20, v20, v155
	v_mul_f32_e32 v21, v21, v155
	v_mul_f32_e32 v22, v22, v155
	v_mul_f32_e32 v23, v23, v155
	v_mul_f32_e32 v24, v24, v155
	v_mul_f32_e32 v25, v25, v155
	v_mul_f32_e32 v26, v26, v155
	v_mul_f32_e32 v27, v27, v155
	v_mul_f32_e32 v28, v28, v155
	v_mul_f32_e32 v29, v29, v155
	v_mul_f32_e32 v30, v30, v155
	v_mul_f32_e32 v31, v31, v155
	v_cvt_pk_bf16_f32 v144, v16, v17
	v_cvt_pk_bf16_f32 v145, v18, v19
	v_cvt_pk_bf16_f32 v148, v20, v21
	v_cvt_pk_bf16_f32 v149, v22, v23
	v_cvt_pk_bf16_f32 v146, v24, v25
	v_cvt_pk_bf16_f32 v147, v26, v27
	v_cvt_pk_bf16_f32 v150, v28, v29
	v_cvt_pk_bf16_f32 v151, v30, v31
	s_nop 1
	v_permlane32_swap_b32_e32 v144, v146
	v_permlane32_swap_b32_e32 v145, v147
	v_permlane32_swap_b32_e32 v148, v150
	v_permlane32_swap_b32_e32 v149, v151
	s_cmp_eq_u32 s16, 0
	s_cbranch_scc0 .Lkv_evd1
	global_store_dwordx4 v244, v[144:147], s[12:13]
	global_store_dwordx4 v244, v[148:151], s[12:13] offset:16
	s_branch .Lkv_eed1

.Lkv_done:
	s_waitcnt vmcnt(0)
	v_mov_b32_e32 v0, v143
	s_and_b64 vcc, exec, s[72:73]
	s_cbranch_vccz .LBB0_419
	v_readlane_b32 s4, v255, 23
	s_mov_b32 s1, 0
	s_mov_b32 s0, 0
	v_readlane_b32 s16, v253, 0
	v_readlane_b32 s5, v255, 24
	s_mov_b32 s17, s4
	s_branch .LBB0_420
